# attnA stage header: persistent per-thread K row pointers advanced by a scalar byte delta instead of recomputing row select + 64-bit mad per stage
# speedup vs baseline: 1.0002x; 1.0002x over previous
; DI void attnA_block(const Params& p, int layer, unsigned char* smem, int b, int h, int qrow_blk, int ubeg, int uend) {
;     ...
;   float gq = lane < 32 ? fabsf(p.da_q_gain[layer * 32 + lane]) : 0.f, gk = lane < 32 ? fabsf(p.da_k_gain[layer * 32 + lane]) : 0.f;
;   gq = wave_max(gq); gk = wave_max(gk);
;   const float negM2 = -(0.17677669529663687f * LOG2E * 32.f * 1.02f) * gq * gk;
;   float la = 0.f, lb_ = 0.f;
;   if (lane < 32) { const float* lv = p.da_lambda + layer * 128; la = lv[lane] * lv[32 + lane]; lb_ = lv[64 + lane] * lv[96 + lane]; }
;   la = wave_sum(la); lb_ = wave_sum(lb_);
;   const float lam = expf(la) - expf(lb_) + lam_init;
;   const bf16_t* qp = p.P + (size_t)(qrow0 + qi) * NP + h * 64 + 8 * hh;
;   bf16x8 qf[2][2];
; #pragma unroll
;   for (int m = 0; m < 2; ++m)
; #pragma unroll
;     for (int ks = 0; ks < 2; ++ks) qf[m][ks] = *(const bf16x8*)(qp + m * 32 + ks * 16);
;   f32x16 o[2][2];
; #pragma unroll
;   for (int m = 0; m < 2; ++m)
; #pragma unroll
;     for (int dh = 0; dh < 2; ++dh)
; #pragma unroll
;       for (int i = 0; i < 16; ++i) o[m][dh][i] = 0.f;
;   float ls[2] = {0.f, 0.f};
;   constexpr int VSTR = 272, KBYTES = 128 * LDS_STRIDE, STG = KBYTES + 64 * VSTR;
;   const int krow = tid >> 3, kch = tid & 7;
;   const int vrow = tid >> 4, vch = tid & 15;
;   const bf16_t* kg = p.P + 256 + h * 64 + kch * 8;
;   const bf16_t* vg = p.VtA + ((size_t)((b * 4 + h) * 64 + vrow)) * UA + vch * 8;
;   u32x4 rk0, rk1, rv0, rv1;
;   rk0 = *(const u32x4*)(kg + (size_t)rowOfU(b, ubeg + krow) * NP);
;   rk1 = *(const u32x4*)(kg + (size_t)rowOfU(b, ubeg + krow + 64) * NP);
;   rv0 = *(const u32x4*)(vg + ubeg);
;   rv1 = *(const u32x4*)(vg + (size_t)32 * UA + ubeg);
;   __syncthreads();
;   asm volatile("" :: "v"(qf[0][0]), "v"(qf[0][1]), "v"(qf[1][0]), "v"(qf[1][1]));
;   {
;     unsigned char* Ks = smem; unsigned char* Vs = smem + KBYTES;
;     *(u32x4*)(Ks + krow * LDS_STRIDE + kch * 16) = rk0; *(u32x4*)(Ks + (krow + 64) * LDS_STRIDE + kch * 16) = rk1;
;     *(u32x4*)(Vs + vrow * VSTR + vch * 16) = rv0; *(u32x4*)(Vs + (vrow + 32) * VSTR + vch * 16) = rv1;
;   }
;   __syncthreads();
;   int buf = 0;
;   for (int u0 = ubeg; u0 < uend; u0 += 128) {
;     const int un = u0 + 128 < uend ? u0 + 128 : ubeg;
;     rk0 = *(const u32x4*)(kg + (size_t)rowOfU(b, un + krow) * NP);
;     rk1 = *(const u32x4*)(kg + (size_t)rowOfU(b, un + krow + 64) * NP);
.LBB0_292:
	s_or_b64 exec, exec, s[2:3]
	s_lshl_b32 s2, s24, 8
	v_readlane_b32 s3, v253, 27
	s_add_i32 s2, s2, s3
	v_and_b32_e32 v28, 31, v2
	v_lshrrev_b32_e32 v240, 5, v6
	v_ashrrev_i32_e32 v6, 1, v2
	v_readlane_b32 s26, v253, 29
	v_and_b32_e32 v6, 0xffffffe0, v6
	v_or_b32_e32 v12, s2, v28
	v_readlane_b32 s27, v253, 30
	v_add_u32_e32 v200, v12, v6
	v_lshlrev_b32_e32 v192, 4, v240
	v_mov_b64_e32 v[12:13], s[26:27]
	v_mad_i64_i32 v[12:13], s[2:3], v200, s20, v[12:13]
	v_lshl_add_u64 v[12:13], v[12:13], 0, v[192:193]
	v_ashrrev_i32_e32 v6, 4, v2
	v_readlane_b32 s2, v253, 23
	global_load_dwordx4 v[144:147], v[12:13], off
	global_load_dwordx4 v[148:151], v[12:13], off offset:32
	global_load_dwordx4 v[152:155], v[12:13], off offset:64
	global_load_dwordx4 v[156:159], v[12:13], off offset:96
	v_lshlrev_b32_e32 v14, 4, v2
	v_add_u32_e32 v15, s2, v6
	v_mov_b64_e32 v[12:13], s[82:83]
	s_mov_b32 s2, 0x8200
	v_ashrrev_i32_e32 v242, 3, v2
	v_mad_i64_i32 v[12:13], s[2:3], v15, s2, v[12:13]
	v_and_b32_e32 v206, 0xf0, v14
	v_mov_b32_e32 v207, v193
	v_readlane_b32 s29, v253, 26
	s_movk_i32 s31, 0x100
	v_lshl_add_u64 v[208:209], v[12:13], 0, v[206:207]
	v_mov_b32_e32 v12, s29
	v_mov_b32_e32 v13, s22
	v_cmp_gt_i32_e32 vcc, s31, v242
	v_readlane_b32 s30, v253, 28
	v_readlane_b32 s28, v253, 25
	v_and_b32_e32 v202, 0x70, v14
	v_cndmask_b32_e32 v12, v12, v13, vcc
	v_mov_b32_e32 v14, s30
	v_mov_b32_e32 v15, s28
	v_cmp_gt_i32_e32 vcc, s42, v242
	v_mov_b32_e32 v203, v193
	v_lshl_add_u64 v[204:205], s[26:27], 0, v[202:203]
	v_cndmask_b32_e32 v14, v14, v15, vcc
	v_add_u32_e32 v12, v12, v242
	v_add_u32_e32 v14, v14, v242
	v_mad_i64_i32 v[12:13], s[2:3], v12, s20, v[204:205]
	v_mad_i64_i32 v[16:17], s[2:3], v14, s20, v[204:205]
	v_add_co_u32_e32 v24, vcc, s62, v208
	global_load_dwordx4 v[12:15], v[12:13], off offset:512
	s_nop 0
	global_load_dwordx4 v[16:19], v[16:17], off offset:512
	s_nop 0
	global_load_dwordx4 v[20:23], v[208:209], off
	v_addc_co_u32_e32 v25, vcc, 0, v209, vcc
	global_load_dwordx4 v[24:27], v[24:25], off
	s_waitcnt lgkmcnt(1)
	v_max_f32_e32 v10, v10, v10
	v_max_f32_e32 v8, v8, v8
	v_max_f32_e32 v8, v8, v10
	s_waitcnt lgkmcnt(0)
	v_max_f32_e32 v10, v11, v11
	v_max_f32_e32 v9, v9, v9
	ds_bpermute_b32 v11, v239, v1
	v_max_f32_e32 v9, v9, v10
	ds_bpermute_b32 v10, v239, v0
	v_mul_f32_e32 v8, 0xc105307d, v8
	v_mul_f32_e32 v64, v8, v9
	s_waitcnt lgkmcnt(1)
	v_add_f32_e32 v1, v1, v11
	ds_bpermute_b32 v8, v3, v1
	s_waitcnt lgkmcnt(1)
	v_add_f32_e32 v0, v0, v10
	ds_bpermute_b32 v3, v3, v0
	s_mov_b64 s[2:3], 0x104000
	v_and_b32_e32 v9, 19, v2
	s_waitcnt lgkmcnt(1)
	v_add_f32_e32 v1, v1, v8
	ds_bpermute_b32 v8, v4, v1
	s_waitcnt lgkmcnt(1)
	v_add_f32_e32 v0, v0, v3
	ds_bpermute_b32 v3, v4, v0
	v_lshlrev_b32_e32 v10, 1, v2
	v_lshrrev_b32_e32 v2, 1, v2
	s_waitcnt lgkmcnt(1)
	v_add_f32_e32 v1, v1, v8
	ds_bpermute_b32 v8, v5, v1
	s_waitcnt lgkmcnt(1)
	v_add_f32_e32 v0, v0, v3
	ds_bpermute_b32 v3, v5, v0
	v_lshl_add_u64 v[210:211], v[208:209], 0, s[2:3]
	v_mul_lo_u32 v246, v242, s59
	s_waitcnt lgkmcnt(1)
	v_add_f32_e32 v207, v1, v8
	ds_bpermute_b32 v243, v7, v207
	s_waitcnt lgkmcnt(1)
	v_add_f32_e32 v244, v0, v3
	ds_bpermute_b32 v245, v7, v244
	s_movk_i32 s2, 0x110
	v_and_b32_e32 v4, 8, v10
	v_and_b32_e32 v2, 4, v2
	v_add_u32_e32 v0, v246, v202
	v_mul_lo_u32 v247, v6, s2
	v_or3_b32 v2, v4, v9, v2
	s_waitcnt lgkmcnt(0)
	s_barrier
	s_waitcnt vmcnt(4)
	s_waitcnt vmcnt(3)
	ds_write_b128 v0, v[12:15]
	s_waitcnt vmcnt(2)
	ds_write_b128 v0, v[16:19] offset:9216
	v_add_u32_e32 v0, v247, v206
	v_ashrrev_i32_e32 v201, 31, v200
	s_mov_b32 s25, 0
	s_waitcnt vmcnt(1)
	ds_write_b128 v0, v[20:23] offset:18432
	s_waitcnt vmcnt(0)
	ds_write_b128 v0, v[24:27] offset:27136
	v_mul_u32_u24_e32 v248, 0x90, v2
	v_mov_b32_e32 v65, v64
	v_mov_b32_e32 v66, v64
	v_mov_b32_e32 v67, v64
	v_mov_b32_e32 v68, v64
	v_mov_b32_e32 v69, v64
	v_mov_b32_e32 v70, v64
	v_mov_b32_e32 v71, v64
	v_mov_b32_e32 v72, v64
	v_mov_b32_e32 v73, v64
	v_mov_b32_e32 v74, v64
	v_mov_b32_e32 v75, v64
	v_mov_b32_e32 v76, v64
	v_mov_b32_e32 v77, v64
	v_mov_b32_e32 v78, v64
	v_mov_b32_e32 v79, v64
	v_mul_u32_u24_e32 v249, 0x110, v28
	v_mov_b32_e32 v203, 0
	s_mov_b32 s2, 0
	v_mov_b32_e32 v0, 0
	v_mov_b32_e32 v1, v199
	v_mov_b32_e32 v2, v199
	v_mov_b32_e32 v3, v199
	v_mov_b32_e32 v4, v199
	v_mov_b32_e32 v5, v199
	v_mov_b32_e32 v6, v199
	v_mov_b32_e32 v7, v199
	v_mov_b32_e32 v8, v199
	v_mov_b32_e32 v9, v199
	v_mov_b32_e32 v10, v199
	v_mov_b32_e32 v11, v199
	v_mov_b32_e32 v12, v199
	v_mov_b32_e32 v13, v199
	v_mov_b32_e32 v14, v199
	v_mov_b32_e32 v15, v199
	v_mov_b32_e32 v32, 0
	v_mov_b32_e32 v33, v199
	v_mov_b32_e32 v34, v199
	v_mov_b32_e32 v35, v199
	v_mov_b32_e32 v36, v199
	v_mov_b32_e32 v37, v199
	v_mov_b32_e32 v38, v199
	v_mov_b32_e32 v39, v199
	v_mov_b32_e32 v40, v199
	v_mov_b32_e32 v41, v199
	v_mov_b32_e32 v42, v199
	v_mov_b32_e32 v43, v199
	v_mov_b32_e32 v44, v199
	v_mov_b32_e32 v45, v199
	v_mov_b32_e32 v46, v199
	v_mov_b32_e32 v47, v199
	v_mov_b32_e32 v16, 0
	v_mov_b32_e32 v17, v199
	v_mov_b32_e32 v18, v199
	v_mov_b32_e32 v19, v199
	v_mov_b32_e32 v20, v199
	v_mov_b32_e32 v21, v199
	v_mov_b32_e32 v22, v199
	v_mov_b32_e32 v23, v199
	v_mov_b32_e32 v24, v199
	v_mov_b32_e32 v25, v199
	v_mov_b32_e32 v26, v199
	v_mov_b32_e32 v27, v199
	v_mov_b32_e32 v28, v199
	v_mov_b32_e32 v29, v199
	v_mov_b32_e32 v30, v199
	v_mov_b32_e32 v31, v199
	v_mov_b32_e32 v48, 0
	v_mov_b32_e32 v49, v199
	v_mov_b32_e32 v50, v199
	v_mov_b32_e32 v51, v199
	v_mov_b32_e32 v52, v199
	v_mov_b32_e32 v53, v199
	v_mov_b32_e32 v54, v199
	v_mov_b32_e32 v55, v199
	v_mov_b32_e32 v56, v199
	v_mov_b32_e32 v57, v199
	v_mov_b32_e32 v58, v199
	v_mov_b32_e32 v59, v199
	v_mov_b32_e32 v60, v199
	v_mov_b32_e32 v61, v199
	v_mov_b32_e32 v62, v199
	v_mov_b32_e32 v63, v199
	s_mov_b32 s27, s22
	s_waitcnt lgkmcnt(0)
	s_barrier
	v_add_u32_e32 v234, s27, v242
	v_add_u32_e32 v236, s28, v242
	s_mov_b32 s44, s27
	v_mad_i64_i32 v[234:235], s[46:47], v234, s20, v[204:205]
	v_mad_i64_i32 v[236:237], s[46:47], v236, s20, v[204:205]
	v_add_u32_e32 v251, v248, v192
	v_add_u32_e32 v250, v249, v192
	ds_read_b128 v[224:227], v251
	ds_read_b128 v[228:231], v251 offset:32
	s_waitcnt lgkmcnt(0)
	v_mfma_f32_32x32x16_bf16 v[80:95], v[224:227], v[144:147], v[64:79]
	v_mfma_f32_32x32x16_bf16 v[80:95], v[228:231], v[148:151], v[80:95]
	ds_read_b128 v[224:227], v251 offset:64
	ds_read_b128 v[228:231], v251 offset:96
	v_mov_b32_e32 v176, 0
	v_mov_b32_e32 v177, 0
	v_mov_b32_e32 v178, 0
	v_mov_b32_e32 v179, 0
	v_mov_b32_e32 v180, 0
	v_mov_b32_e32 v181, 0
	v_mov_b32_e32 v182, 0
	v_mov_b32_e32 v183, 0
	v_mov_b32_e32 v184, 0
	v_mov_b32_e32 v185, 0
	v_mov_b32_e32 v186, 0
	v_mov_b32_e32 v187, 0
	v_mov_b32_e32 v188, 0
	v_mov_b32_e32 v189, 0
	v_mov_b32_e32 v190, 0
	v_mov_b32_e32 v191, 0
	v_mov_b32_e32 v128, 0
	v_mov_b32_e32 v129, 0
	v_mov_b32_e32 v130, 0
	v_mov_b32_e32 v131, 0
	v_mov_b32_e32 v132, 0
	v_mov_b32_e32 v133, 0
	v_mov_b32_e32 v134, 0
	v_mov_b32_e32 v135, 0
; #define MFMA32(a, b, c) __builtin_amdgcn_mfma_f32_32x32x16_bf16((a), (b), (c), 0, 0, 0)
; DI unsigned pk2(float a, float b) { f32x2 v = {a, b}; return __builtin_bit_cast(unsigned, __builtin_convertvector(v, bf16x2_t)); }
; DI float fexp2(float x) { return __builtin_amdgcn_exp2f(x); }
; DI void attnA_block(const Params& p, int layer, unsigned char* smem, int b, int h, int qrow_blk, int ubeg, int uend) {
;     ...
;   for (int u0 = ubeg; u0 < uend; u0 += 128) {
;     const int un = u0 + 128 < uend ? u0 + 128 : ubeg;
;     rk0 = *(const u32x4*)(kg + (size_t)rowOfU(b, un + krow) * NP);
;     rk1 = *(const u32x4*)(kg + (size_t)rowOfU(b, un + krow + 64) * NP);
;     rv0 = *(const u32x4*)(vg + un);
;     rv1 = *(const u32x4*)(vg + (size_t)32 * UA + un);
;     const unsigned char* Ks = smem + buf * STG;
;     const unsigned char* Vs = Ks + KBYTES;
;     f32x16 sc[2], sn[2];
;     ...
;     A_QK(0, sc);
; #pragma unroll
;     for (int sub = 0; sub < 4; ++sub) {
;       if (sub < 3) A_QK(sub + 1, sn);
;       bf16x8 vf[2][2];
; #pragma unroll
;       for (int dh = 0; dh < 2; ++dh)
; #pragma unroll
;         for (int s2 = 0; s2 < 2; ++s2) vf[dh][s2] = *(const bf16x8*)(Vs + (32 * dh + qi) * VSTR + (32 * sub + 16 * s2 + 8 * hh) * 2);
; #pragma unroll
;       for (int m = 0; m < 2; ++m) {
;         float pe[16];
; #pragma unroll
;         for (int i = 0; i < 16; ++i) pe[i] = fexp2(sc[m][i]);
;         sum16_nopk(ls[m], pe);
; #pragma unroll
;         for (int s2 = 0; s2 < 2; ++s2) {
;           u32x4 pw;
; #pragma unroll
;           for (int q = 0; q < 4; ++q) pw[q] = pk2(pe[8 * s2 + 2 * q], pe[8 * s2 + 2 * q + 1]);
;           const bf16x8 pf = __builtin_bit_cast(bf16x8, pw);
; #pragma unroll
;           for (int dh = 0; dh < 2; ++dh) o[m][dh] = MFMA32(vf[dh][s2], pf, o[m][dh]);
;         }
;       }
;       if (sub < 3) { sc[0] = sn[0]; sc[1] = sn[1]; }
.LBB0_293:
	s_add_i32 s26, s2, 0x80
	s_cmpk_lt_u32 s2, 0x4080
	s_cselect_b64 s[2:3], -1, 0
	s_and_b64 vcc, s[2:3], exec
	s_cselect_b32 s22, s26, 0
	s_cmp_lt_i32 s22, s31
	s_cselect_b32 s45, s27, s29
	s_add_i32 s45, s45, s22
	s_sub_i32 s46, s45, s44
	s_mov_b32 s44, s45
	s_mul_i32 s46, s46, s20
	s_ashr_i32 s47, s46, 31
	v_lshl_add_u64 v[234:235], v[234:235], 0, s[46:47]
	v_lshl_add_u64 v[236:237], v[236:237], 0, s[46:47]
	global_load_dwordx4 v[160:163], v[234:235], off offset:512
	global_load_dwordx4 v[164:167], v[236:237], off offset:512
	s_lshl_b64 s[2:3], s[22:23], 1
	v_lshl_add_u64 v[232:233], v[208:209], 0, s[2:3]
	global_load_dwordx4 v[168:171], v[232:233], off
	v_lshl_add_u64 v[232:233], v[210:211], 0, s[2:3]
	global_load_dwordx4 v[172:175], v[232:233], off
	s_xor_b32 s25, s25, 1
	s_mul_i32 s2, s25, 0x8c00
	s_waitcnt lgkmcnt(0)
	v_mfma_f32_32x32x16_bf16 v[96:111], v[224:227], v[152:155], v[64:79]
	v_exp_f32_e32 v80, v80
	v_exp_f32_e32 v81, v81
	v_exp_f32_e32 v82, v82
	v_add_f32_e32 v203, v80, v203
	v_exp_f32_e32 v83, v83
	v_mfma_f32_32x32x16_bf16 v[96:111], v[228:231], v[156:159], v[96:111]
	ds_read_b128 v[224:227], v251 offset:4608
	ds_read_b128 v[228:231], v251 offset:4640
	v_add_f32_e32 v203, v81, v203
	v_cvt_pk_bf16_f32 v80, v80, v81
	v_exp_f32_e32 v84, v84
	v_add_f32_e32 v203, v82, v203
	v_exp_f32_e32 v85, v85
	v_add_f32_e32 v203, v83, v203
	v_cvt_pk_bf16_f32 v81, v82, v83
	s_waitcnt lgkmcnt(6)
	v_mfma_f32_32x32x16_bf16 v[32:47], v[176:179], v[128:131], v[32:47]
	ds_read_b128 v[176:179], v250 offset:18432
	v_exp_f32_e32 v86, v86
	v_add_f32_e32 v203, v84, v203
	v_exp_f32_e32 v87, v87
	v_add_f32_e32 v203, v85, v203
	v_cvt_pk_bf16_f32 v82, v84, v85
	v_exp_f32_e32 v88, v88
	v_add_f32_e32 v203, v86, v203
	s_waitcnt lgkmcnt(7)
	v_mfma_f32_32x32x16_bf16 v[0:15], v[184:187], v[128:131], v[0:15]
	ds_read_b128 v[184:187], v250 offset:27136
	v_exp_f32_e32 v89, v89
	v_add_f32_e32 v203, v87, v203
	v_cvt_pk_bf16_f32 v83, v86, v87
	v_exp_f32_e32 v90, v90
	v_add_f32_e32 v203, v88, v203
	v_exp_f32_e32 v91, v91
	s_waitcnt lgkmcnt(8)
	v_mfma_f32_32x32x16_bf16 v[32:47], v[180:183], v[132:135], v[32:47]
	ds_read_b128 v[180:183], v250 offset:18464
	v_add_f32_e32 v203, v89, v203
	v_cvt_pk_bf16_f32 v84, v88, v89
	v_exp_f32_e32 v92, v92
	v_add_f32_e32 v203, v90, v203
	v_exp_f32_e32 v93, v93
	v_add_f32_e32 v203, v91, v203
	v_cvt_pk_bf16_f32 v85, v90, v91
	s_waitcnt lgkmcnt(9)
	v_mfma_f32_32x32x16_bf16 v[0:15], v[188:191], v[132:135], v[0:15]
	ds_read_b128 v[188:191], v250 offset:27168
	v_exp_f32_e32 v94, v94
	v_add_f32_e32 v203, v92, v203
	v_exp_f32_e32 v95, v95
	v_add_f32_e32 v203, v93, v203
	v_cvt_pk_bf16_f32 v86, v92, v93
	v_add_f32_e32 v203, v94, v203
	v_add_f32_e32 v203, v95, v203
	v_cvt_pk_bf16_f32 v87, v94, v95
	s_waitcnt lgkmcnt(4)
	v_mfma_f32_32x32x16_bf16 v[112:127], v[224:227], v[144:147], v[64:79]
	v_exp_f32_e32 v96, v96
	v_exp_f32_e32 v97, v97
	v_exp_f32_e32 v98, v98
	v_add_f32_e32 v199, v96, v199
	v_exp_f32_e32 v99, v99
	v_mfma_f32_32x32x16_bf16 v[112:127], v[228:231], v[148:151], v[112:127]
	ds_read_b128 v[224:227], v251 offset:4672
	ds_read_b128 v[228:231], v251 offset:4704
	v_add_f32_e32 v199, v97, v199
	v_cvt_pk_bf16_f32 v96, v96, v97
	v_exp_f32_e32 v100, v100
	v_add_f32_e32 v199, v98, v199
	v_exp_f32_e32 v101, v101
	v_add_f32_e32 v199, v99, v199
	v_cvt_pk_bf16_f32 v97, v98, v99
	s_waitcnt lgkmcnt(5)
	v_mfma_f32_32x32x16_bf16 v[48:63], v[176:179], v[80:83], v[48:63]
	v_exp_f32_e32 v102, v102
	v_add_f32_e32 v199, v100, v199
	v_exp_f32_e32 v103, v103
	v_add_f32_e32 v199, v101, v199
	v_cvt_pk_bf16_f32 v98, v100, v101
	v_exp_f32_e32 v104, v104
	v_add_f32_e32 v199, v102, v199
	s_waitcnt lgkmcnt(4)
	v_mfma_f32_32x32x16_bf16 v[16:31], v[184:187], v[80:83], v[16:31]
	v_exp_f32_e32 v105, v105
	v_add_f32_e32 v199, v103, v199
	v_cvt_pk_bf16_f32 v99, v102, v103
	v_exp_f32_e32 v106, v106
	v_add_f32_e32 v199, v104, v199
	v_exp_f32_e32 v107, v107
	s_waitcnt lgkmcnt(3)
	v_mfma_f32_32x32x16_bf16 v[48:63], v[180:183], v[84:87], v[48:63]
	v_add_f32_e32 v199, v105, v199
	v_cvt_pk_bf16_f32 v100, v104, v105
	v_exp_f32_e32 v108, v108
	v_add_f32_e32 v199, v106, v199
	v_exp_f32_e32 v109, v109
	v_add_f32_e32 v199, v107, v199
	v_cvt_pk_bf16_f32 v101, v106, v107
	s_waitcnt lgkmcnt(2)
	v_mfma_f32_32x32x16_bf16 v[16:31], v[188:191], v[84:87], v[16:31]
	v_exp_f32_e32 v110, v110
	v_add_f32_e32 v199, v108, v199
	v_exp_f32_e32 v111, v111
	v_add_f32_e32 v199, v109, v199
	v_cvt_pk_bf16_f32 v102, v108, v109
	v_add_f32_e32 v199, v110, v199
	v_add_f32_e32 v199, v111, v199
	v_cvt_pk_bf16_f32 v103, v110, v111
	s_waitcnt lgkmcnt(0)
	v_mfma_f32_32x32x16_bf16 v[128:143], v[224:227], v[152:155], v[64:79]
	v_exp_f32_e32 v112, v112
	v_exp_f32_e32 v113, v113
	v_exp_f32_e32 v114, v114
	v_add_f32_e32 v203, v112, v203
	v_exp_f32_e32 v115, v115
	v_mfma_f32_32x32x16_bf16 v[128:143], v[228:231], v[156:159], v[128:143]
	ds_read_b128 v[224:227], v251 offset:9216
	ds_read_b128 v[228:231], v251 offset:9248
	v_add_f32_e32 v203, v113, v203
	v_cvt_pk_bf16_f32 v112, v112, v113
	v_exp_f32_e32 v116, v116
	v_add_f32_e32 v203, v114, v203
	v_exp_f32_e32 v117, v117
	v_add_f32_e32 v203, v115, v203
	v_cvt_pk_bf16_f32 v113, v114, v115
	s_waitcnt lgkmcnt(7)
	v_mfma_f32_32x32x16_bf16 v[32:47], v[176:179], v[96:99], v[32:47]
	ds_read_b128 v[176:179], v250 offset:18496
	v_exp_f32_e32 v118, v118
	v_add_f32_e32 v203, v116, v203
	v_exp_f32_e32 v119, v119
	v_add_f32_e32 v203, v117, v203
	v_cvt_pk_bf16_f32 v114, v116, v117
	v_exp_f32_e32 v120, v120
	v_add_f32_e32 v203, v118, v203
	s_waitcnt lgkmcnt(7)
; #define MFMA32(a, b, c) __builtin_amdgcn_mfma_f32_32x32x16_bf16((a), (b), (c), 0, 0, 0)
; DI unsigned pk2(float a, float b) { f32x2 v = {a, b}; return __builtin_bit_cast(unsigned, __builtin_convertvector(v, bf16x2_t)); }
; DI float fexp2(float x) { return __builtin_amdgcn_exp2f(x); }
; DI void attnA_block(const Params& p, int layer, unsigned char* smem, int b, int h, int qrow_blk, int ubeg, int uend) {
;     ...
;     for (int sub = 0; sub < 4; ++sub) {
;       if (sub < 3) A_QK(sub + 1, sn);
;       bf16x8 vf[2][2];
; #pragma unroll
;       for (int dh = 0; dh < 2; ++dh)
; #pragma unroll
;         for (int s2 = 0; s2 < 2; ++s2) vf[dh][s2] = *(const bf16x8*)(Vs + (32 * dh + qi) * VSTR + (32 * sub + 16 * s2 + 8 * hh) * 2);
; #pragma unroll
;       for (int m = 0; m < 2; ++m) {
;         float pe[16];
; #pragma unroll
;         for (int i = 0; i < 16; ++i) pe[i] = fexp2(sc[m][i]);
;         sum16_nopk(ls[m], pe);
; #pragma unroll
;         for (int s2 = 0; s2 < 2; ++s2) {
;           u32x4 pw;
; #pragma unroll
;           for (int q = 0; q < 4; ++q) pw[q] = pk2(pe[8 * s2 + 2 * q], pe[8 * s2 + 2 * q + 1]);
;           const bf16x8 pf = __builtin_bit_cast(bf16x8, pw);
; #pragma unroll
;           for (int dh = 0; dh < 2; ++dh) o[m][dh] = MFMA32(vf[dh][s2], pf, o[m][dh]);
;         }
;       }
;       if (sub < 3) { sc[0] = sn[0]; sc[1] = sn[1]; }
	v_mfma_f32_32x32x16_bf16 v[0:15], v[184:187], v[96:99], v[0:15]
	ds_read_b128 v[184:187], v250 offset:27200
	v_exp_f32_e32 v121, v121
	v_add_f32_e32 v203, v119, v203
	v_cvt_pk_bf16_f32 v115, v118, v119
	v_exp_f32_e32 v122, v122
	v_add_f32_e32 v203, v120, v203
	v_exp_f32_e32 v123, v123
	s_waitcnt lgkmcnt(7)
	v_mfma_f32_32x32x16_bf16 v[32:47], v[180:183], v[100:103], v[32:47]
	ds_read_b128 v[180:183], v250 offset:18528
	v_add_f32_e32 v203, v121, v203
	v_cvt_pk_bf16_f32 v116, v120, v121
	v_exp_f32_e32 v124, v124
	v_add_f32_e32 v203, v122, v203
	v_exp_f32_e32 v125, v125
	v_add_f32_e32 v203, v123, v203
	v_cvt_pk_bf16_f32 v117, v122, v123
	s_waitcnt lgkmcnt(7)
	v_mfma_f32_32x32x16_bf16 v[0:15], v[188:191], v[100:103], v[0:15]
	ds_read_b128 v[188:191], v250 offset:27232
	v_exp_f32_e32 v126, v126
	v_add_f32_e32 v203, v124, v203
	v_exp_f32_e32 v127, v127
	v_add_f32_e32 v203, v125, v203
	v_cvt_pk_bf16_f32 v118, v124, v125
	v_add_f32_e32 v203, v126, v203
	v_add_f32_e32 v203, v127, v203
	v_cvt_pk_bf16_f32 v119, v126, v127
	s_waitcnt lgkmcnt(4)
	v_mfma_f32_32x32x16_bf16 v[80:95], v[224:227], v[144:147], v[64:79]
	v_exp_f32_e32 v128, v128
	v_exp_f32_e32 v129, v129
	v_exp_f32_e32 v130, v130
	v_add_f32_e32 v199, v128, v199
	v_exp_f32_e32 v131, v131
	v_mfma_f32_32x32x16_bf16 v[80:95], v[228:231], v[148:151], v[80:95]
	ds_read_b128 v[224:227], v251 offset:9280
	ds_read_b128 v[228:231], v251 offset:9312
	v_add_f32_e32 v199, v129, v199
	v_cvt_pk_bf16_f32 v128, v128, v129
	v_exp_f32_e32 v132, v132
	v_add_f32_e32 v199, v130, v199
	v_exp_f32_e32 v133, v133
	v_add_f32_e32 v199, v131, v199
	v_cvt_pk_bf16_f32 v129, v130, v131
	s_waitcnt lgkmcnt(5)
	v_mfma_f32_32x32x16_bf16 v[48:63], v[176:179], v[112:115], v[48:63]
	v_exp_f32_e32 v134, v134
	v_add_f32_e32 v199, v132, v199
	v_exp_f32_e32 v135, v135
	v_add_f32_e32 v199, v133, v199
	v_cvt_pk_bf16_f32 v130, v132, v133
	v_exp_f32_e32 v136, v136
	v_add_f32_e32 v199, v134, v199
	s_waitcnt lgkmcnt(4)
	v_mfma_f32_32x32x16_bf16 v[16:31], v[184:187], v[112:115], v[16:31]
	v_exp_f32_e32 v137, v137
	v_add_f32_e32 v199, v135, v199
	v_cvt_pk_bf16_f32 v131, v134, v135
	v_exp_f32_e32 v138, v138
	v_add_f32_e32 v199, v136, v199
	v_exp_f32_e32 v139, v139
	s_waitcnt lgkmcnt(3)
	v_mfma_f32_32x32x16_bf16 v[48:63], v[180:183], v[116:119], v[48:63]
	v_add_f32_e32 v199, v137, v199
	v_cvt_pk_bf16_f32 v132, v136, v137
	v_exp_f32_e32 v140, v140
	v_add_f32_e32 v199, v138, v199
	v_exp_f32_e32 v141, v141
	v_add_f32_e32 v199, v139, v199
	v_cvt_pk_bf16_f32 v133, v138, v139
	s_waitcnt lgkmcnt(2)
	v_mfma_f32_32x32x16_bf16 v[16:31], v[188:191], v[116:119], v[16:31]
	v_exp_f32_e32 v142, v142
	v_add_f32_e32 v199, v140, v199
	v_exp_f32_e32 v143, v143
	v_add_f32_e32 v199, v141, v199
	v_cvt_pk_bf16_f32 v134, v140, v141
	v_add_f32_e32 v199, v142, v199
	v_add_f32_e32 v199, v143, v199
	v_cvt_pk_bf16_f32 v135, v142, v143
	s_waitcnt lgkmcnt(0)
	v_mfma_f32_32x32x16_bf16 v[96:111], v[224:227], v[152:155], v[64:79]
	v_exp_f32_e32 v80, v80
	v_exp_f32_e32 v81, v81
	v_exp_f32_e32 v82, v82
	v_add_f32_e32 v203, v80, v203
	v_exp_f32_e32 v83, v83
	v_mfma_f32_32x32x16_bf16 v[96:111], v[228:231], v[156:159], v[96:111]
	ds_read_b128 v[224:227], v251 offset:13824
	ds_read_b128 v[228:231], v251 offset:13856
	v_add_f32_e32 v203, v81, v203
	v_cvt_pk_bf16_f32 v80, v80, v81
	v_exp_f32_e32 v84, v84
	v_add_f32_e32 v203, v82, v203
	v_exp_f32_e32 v85, v85
	v_add_f32_e32 v203, v83, v203
	v_cvt_pk_bf16_f32 v81, v82, v83
	s_waitcnt lgkmcnt(7)
	v_mfma_f32_32x32x16_bf16 v[32:47], v[176:179], v[128:131], v[32:47]
	ds_read_b128 v[176:179], v250 offset:18560
	v_exp_f32_e32 v86, v86
	v_add_f32_e32 v203, v84, v203
	v_exp_f32_e32 v87, v87
	v_add_f32_e32 v203, v85, v203
	v_cvt_pk_bf16_f32 v82, v84, v85
	v_exp_f32_e32 v88, v88
	v_add_f32_e32 v203, v86, v203
	s_waitcnt lgkmcnt(7)
	v_mfma_f32_32x32x16_bf16 v[0:15], v[184:187], v[128:131], v[0:15]
	ds_read_b128 v[184:187], v250 offset:27264
	v_exp_f32_e32 v89, v89
	v_add_f32_e32 v203, v87, v203
	v_cvt_pk_bf16_f32 v83, v86, v87
	v_exp_f32_e32 v90, v90
	v_add_f32_e32 v203, v88, v203
	v_exp_f32_e32 v91, v91
	s_waitcnt lgkmcnt(7)
	v_mfma_f32_32x32x16_bf16 v[32:47], v[180:183], v[132:135], v[32:47]
	ds_read_b128 v[180:183], v250 offset:18592
	v_add_f32_e32 v203, v89, v203
	v_cvt_pk_bf16_f32 v84, v88, v89
	v_exp_f32_e32 v92, v92
	v_add_f32_e32 v203, v90, v203
	v_exp_f32_e32 v93, v93
	v_add_f32_e32 v203, v91, v203
	v_cvt_pk_bf16_f32 v85, v90, v91
	s_waitcnt lgkmcnt(7)
	v_mfma_f32_32x32x16_bf16 v[0:15], v[188:191], v[132:135], v[0:15]
	ds_read_b128 v[188:191], v250 offset:27296
	v_exp_f32_e32 v94, v94
	v_add_f32_e32 v203, v92, v203
	v_exp_f32_e32 v95, v95
	v_add_f32_e32 v203, v93, v203
	v_cvt_pk_bf16_f32 v86, v92, v93
	v_add_f32_e32 v203, v94, v203
	v_add_f32_e32 v203, v95, v203
	v_cvt_pk_bf16_f32 v87, v94, v95
	s_waitcnt lgkmcnt(4)
	v_mfma_f32_32x32x16_bf16 v[112:127], v[224:227], v[144:147], v[64:79]
	v_exp_f32_e32 v96, v96
	v_exp_f32_e32 v97, v97
	v_exp_f32_e32 v98, v98
	v_add_f32_e32 v199, v96, v199
	v_exp_f32_e32 v99, v99
	v_mfma_f32_32x32x16_bf16 v[112:127], v[228:231], v[148:151], v[112:127]
	ds_read_b128 v[224:227], v251 offset:13888
	ds_read_b128 v[228:231], v251 offset:13920
	v_add_f32_e32 v199, v97, v199
	v_cvt_pk_bf16_f32 v96, v96, v97
	v_exp_f32_e32 v100, v100
	v_add_f32_e32 v199, v98, v199
	v_exp_f32_e32 v101, v101
	v_add_f32_e32 v199, v99, v199
	v_cvt_pk_bf16_f32 v97, v98, v99
	s_waitcnt lgkmcnt(5)
	v_mfma_f32_32x32x16_bf16 v[48:63], v[176:179], v[80:83], v[48:63]
	v_exp_f32_e32 v102, v102
	v_add_f32_e32 v199, v100, v199
	v_exp_f32_e32 v103, v103
	v_add_f32_e32 v199, v101, v199
	v_cvt_pk_bf16_f32 v98, v100, v101
	v_exp_f32_e32 v104, v104
	v_add_f32_e32 v199, v102, v199
	s_waitcnt lgkmcnt(4)
; #define MFMA32(a, b, c) __builtin_amdgcn_mfma_f32_32x32x16_bf16((a), (b), (c), 0, 0, 0)
; DI unsigned pk2(float a, float b) { f32x2 v = {a, b}; return __builtin_bit_cast(unsigned, __builtin_convertvector(v, bf16x2_t)); }
; DI float fexp2(float x) { return __builtin_amdgcn_exp2f(x); }
; DI void attnA_block(const Params& p, int layer, unsigned char* smem, int b, int h, int qrow_blk, int ubeg, int uend) {
;     ...
;     for (int sub = 0; sub < 4; ++sub) {
;       if (sub < 3) A_QK(sub + 1, sn);
;       bf16x8 vf[2][2];
; #pragma unroll
;       for (int dh = 0; dh < 2; ++dh)
; #pragma unroll
;         for (int s2 = 0; s2 < 2; ++s2) vf[dh][s2] = *(const bf16x8*)(Vs + (32 * dh + qi) * VSTR + (32 * sub + 16 * s2 + 8 * hh) * 2);
; #pragma unroll
;       for (int m = 0; m < 2; ++m) {
;         float pe[16];
; #pragma unroll
;         for (int i = 0; i < 16; ++i) pe[i] = fexp2(sc[m][i]);
;         sum16_nopk(ls[m], pe);
; #pragma unroll
;         for (int s2 = 0; s2 < 2; ++s2) {
;           u32x4 pw;
; #pragma unroll
;           for (int q = 0; q < 4; ++q) pw[q] = pk2(pe[8 * s2 + 2 * q], pe[8 * s2 + 2 * q + 1]);
;           const bf16x8 pf = __builtin_bit_cast(bf16x8, pw);
; #pragma unroll
;           for (int dh = 0; dh < 2; ++dh) o[m][dh] = MFMA32(vf[dh][s2], pf, o[m][dh]);
;         }
;       }
;       if (sub < 3) { sc[0] = sn[0]; sc[1] = sn[1]; }
;     }
;     {
;       unsigned char* Kw = smem + (buf ^ 1) * STG; unsigned char* Vw = Kw + KBYTES;
;       *(u32x4*)(Kw + krow * LDS_STRIDE + kch * 16) = rk0; *(u32x4*)(Kw + (krow + 64) * LDS_STRIDE + kch * 16) = rk1;
;       *(u32x4*)(Vw + vrow * VSTR + vch * 16) = rv0; *(u32x4*)(Vw + (vrow + 32) * VSTR + vch * 16) = rv1;
;     }
;     __syncthreads();
;     buf ^= 1;
;   }
	v_mfma_f32_32x32x16_bf16 v[16:31], v[184:187], v[80:83], v[16:31]
	v_exp_f32_e32 v105, v105
	v_add_f32_e32 v199, v103, v199
	v_cvt_pk_bf16_f32 v99, v102, v103
	v_exp_f32_e32 v106, v106
	v_add_f32_e32 v199, v104, v199
	v_exp_f32_e32 v107, v107
	s_waitcnt lgkmcnt(3)
	v_mfma_f32_32x32x16_bf16 v[48:63], v[180:183], v[84:87], v[48:63]
	v_add_f32_e32 v199, v105, v199
	v_cvt_pk_bf16_f32 v100, v104, v105
	v_exp_f32_e32 v108, v108
	v_add_f32_e32 v199, v106, v199
	v_exp_f32_e32 v109, v109
	v_add_f32_e32 v199, v107, v199
	v_cvt_pk_bf16_f32 v101, v106, v107
	s_waitcnt lgkmcnt(2)
	v_mfma_f32_32x32x16_bf16 v[16:31], v[188:191], v[84:87], v[16:31]
	v_exp_f32_e32 v110, v110
	v_add_f32_e32 v199, v108, v199
	v_exp_f32_e32 v111, v111
	v_add_f32_e32 v199, v109, v199
	v_cvt_pk_bf16_f32 v102, v108, v109
	v_add_f32_e32 v199, v110, v199
	v_add_f32_e32 v199, v111, v199
	v_cvt_pk_bf16_f32 v103, v110, v111
	s_waitcnt lgkmcnt(0)
	v_mfma_f32_32x32x16_bf16 v[128:143], v[224:227], v[152:155], v[64:79]
	v_exp_f32_e32 v112, v112
	v_exp_f32_e32 v113, v113
	v_exp_f32_e32 v114, v114
	v_add_f32_e32 v203, v112, v203
	v_exp_f32_e32 v115, v115
	v_mfma_f32_32x32x16_bf16 v[128:143], v[228:231], v[156:159], v[128:143]
	v_add_f32_e32 v203, v113, v203
	v_cvt_pk_bf16_f32 v112, v112, v113
	v_exp_f32_e32 v116, v116
	v_add_f32_e32 v203, v114, v203
	v_exp_f32_e32 v117, v117
	v_add_f32_e32 v203, v115, v203
	v_cvt_pk_bf16_f32 v113, v114, v115
	s_waitcnt lgkmcnt(5)
	v_mfma_f32_32x32x16_bf16 v[32:47], v[176:179], v[96:99], v[32:47]
	ds_read_b128 v[176:179], v250 offset:18624
	v_exp_f32_e32 v118, v118
	v_add_f32_e32 v203, v116, v203
	v_exp_f32_e32 v119, v119
	v_add_f32_e32 v203, v117, v203
	v_cvt_pk_bf16_f32 v114, v116, v117
	v_exp_f32_e32 v120, v120
	v_add_f32_e32 v203, v118, v203
	s_waitcnt lgkmcnt(5)
	v_mfma_f32_32x32x16_bf16 v[0:15], v[184:187], v[96:99], v[0:15]
	ds_read_b128 v[184:187], v250 offset:27328
	v_exp_f32_e32 v121, v121
	v_add_f32_e32 v203, v119, v203
	v_cvt_pk_bf16_f32 v115, v118, v119
	v_exp_f32_e32 v122, v122
	v_add_f32_e32 v203, v120, v203
	v_exp_f32_e32 v123, v123
	s_waitcnt lgkmcnt(5)
	v_mfma_f32_32x32x16_bf16 v[32:47], v[180:183], v[100:103], v[32:47]
	ds_read_b128 v[180:183], v250 offset:18656
	v_add_f32_e32 v203, v121, v203
	v_cvt_pk_bf16_f32 v116, v120, v121
	v_exp_f32_e32 v124, v124
	v_add_f32_e32 v203, v122, v203
	v_exp_f32_e32 v125, v125
	v_add_f32_e32 v203, v123, v203
	v_cvt_pk_bf16_f32 v117, v122, v123
	s_waitcnt lgkmcnt(5)
	v_mfma_f32_32x32x16_bf16 v[0:15], v[188:191], v[100:103], v[0:15]
	ds_read_b128 v[188:191], v250 offset:27360
	v_exp_f32_e32 v126, v126
	v_add_f32_e32 v203, v124, v203
	v_exp_f32_e32 v127, v127
	v_add_f32_e32 v203, v125, v203
	v_cvt_pk_bf16_f32 v118, v124, v125
	v_add_f32_e32 v203, v126, v203
	v_add_f32_e32 v203, v127, v203
	v_cvt_pk_bf16_f32 v119, v126, v127
	s_waitcnt lgkmcnt(3)
	v_mfma_f32_32x32x16_bf16 v[48:63], v[176:179], v[112:115], v[48:63]
	v_exp_f32_e32 v128, v128
	v_exp_f32_e32 v129, v129
	v_exp_f32_e32 v130, v130
	v_add_f32_e32 v199, v128, v199
	v_exp_f32_e32 v131, v131
	s_waitcnt lgkmcnt(2)
	v_mfma_f32_32x32x16_bf16 v[16:31], v[184:187], v[112:115], v[16:31]
	v_add_f32_e32 v199, v129, v199
	v_cvt_pk_bf16_f32 v128, v128, v129
	v_exp_f32_e32 v132, v132
	v_add_f32_e32 v199, v130, v199
	v_exp_f32_e32 v133, v133
	v_add_f32_e32 v199, v131, v199
	v_cvt_pk_bf16_f32 v129, v130, v131
	v_add3_u32 v232, s2, v246, v202
	s_waitcnt vmcnt(3)
	ds_write_b128 v232, v[160:163]
	s_waitcnt vmcnt(2)
	ds_write_b128 v232, v[164:167] offset:9216
	v_add3_u32 v232, s2, v247, v206
	s_waitcnt vmcnt(1)
	ds_write_b128 v232, v[168:171] offset:18432
	s_waitcnt vmcnt(0)
	ds_write_b128 v232, v[172:175] offset:27136
	v_add3_u32 v251, s2, v248, v192
	v_add3_u32 v250, s2, v249, v192
	s_waitcnt lgkmcnt(0)
	s_barrier
	ds_read_b128 v[224:227], v251
	ds_read_b128 v[228:231], v251 offset:32
	v_mfma_f32_32x32x16_bf16 v[48:63], v[180:183], v[116:119], v[48:63]
	v_exp_f32_e32 v134, v134
	v_add_f32_e32 v199, v132, v199
	v_exp_f32_e32 v135, v135
	v_add_f32_e32 v199, v133, v199
	v_cvt_pk_bf16_f32 v130, v132, v133
	v_exp_f32_e32 v136, v136
	v_add_f32_e32 v199, v134, v199
	v_mfma_f32_32x32x16_bf16 v[16:31], v[188:191], v[116:119], v[16:31]
	v_exp_f32_e32 v137, v137
	v_add_f32_e32 v199, v135, v199
	v_cvt_pk_bf16_f32 v131, v134, v135
	v_exp_f32_e32 v138, v138
	v_add_f32_e32 v199, v136, v199
	v_exp_f32_e32 v139, v139
	s_waitcnt lgkmcnt(0)
	v_mfma_f32_32x32x16_bf16 v[80:95], v[224:227], v[144:147], v[64:79]
	v_mfma_f32_32x32x16_bf16 v[80:95], v[228:231], v[148:151], v[80:95]
	ds_read_b128 v[224:227], v251 offset:64
	ds_read_b128 v[228:231], v251 offset:96
	v_add_f32_e32 v199, v137, v199
	v_cvt_pk_bf16_f32 v132, v136, v137
	v_exp_f32_e32 v140, v140
	v_add_f32_e32 v199, v138, v199
	v_exp_f32_e32 v141, v141
	v_add_f32_e32 v199, v139, v199
	v_cvt_pk_bf16_f32 v133, v138, v139
	v_exp_f32_e32 v142, v142
	v_add_f32_e32 v199, v140, v199
	v_exp_f32_e32 v143, v143
	v_add_f32_e32 v199, v141, v199
	v_cvt_pk_bf16_f32 v134, v140, v141
	v_add_f32_e32 v199, v142, v199
	v_add_f32_e32 v199, v143, v199
	v_cvt_pk_bf16_f32 v135, v142, v143
	s_mov_b32 s2, s26
	s_cbranch_vccnz .LBB0_293
; DI void attnA_block(const Params& p, int layer, unsigned char* smem, int b, int h, int qrow_blk, int ubeg, int uend) {
;     ...
;   float la = 0.f, lb_ = 0.f;
;   if (lane < 32) { const float* lv = p.da_lambda + layer * 128; la = lv[lane] * lv[32 + lane]; lb_ = lv[64 + lane] * lv[96 + lane]; }
;   la = wave_sum(la); lb_ = wave_sum(lb_);
;   const float lam = expf(la) - expf(lb_) + lam_init;
;     ...
;   const float l0 = ls[0] + __shfl_xor(ls[0], 32), l1 = ls[1] + __shfl_xor(ls[1], 32);
;   const float i0 = 1.f / l0, c1 = lam / l1;
;   float ss = 0.f;
; #pragma unroll
;   for (int dh = 0; dh < 2; ++dh)
; #pragma unroll
;     for (int i = 0; i < 16; ++i) { const float v = o[0][dh][i] * i0 - o[1][dh][i] * c1; o[0][dh][i] = v; ss += v * v; }
;   ss += __shfl_xor(ss, 32);
;   const float r = rsqrtf(ss * (1.f / 64.f) + EPS) * (1.f - lam_init);
	v_mfma_f32_32x32x16_bf16 v[32:47], v[176:179], v[128:131], v[32:47]
	v_mfma_f32_32x32x16_bf16 v[0:15], v[184:187], v[128:131], v[0:15]
	v_mfma_f32_32x32x16_bf16 v[32:47], v[180:183], v[132:135], v[32:47]
	v_mfma_f32_32x32x16_bf16 v[0:15], v[188:191], v[132:135], v[0:15]
	s_waitcnt lgkmcnt(0)
	v_mov_b32_e32 v224, 0x900
	v_mov_b32_e32 v225, 0xa0
	v_mov_b32_e32 v226, 0x98
	v_mov_b32_e32 v227, 0x3e38aa3b
	v_mov_b32_e32 v228, 0x800
	v_mov_b32_e32 v229, 0x58
	v_mov_b32_e32 v230, 0x50
	v_mov_b32_e32 v231, 0x3e8293ee
	v_mov_b32_e32 v233, 0x7f800000
	v_mov_b32_e32 v234, 0x120
	v_mov_b32_e32 v235, 0x100
	v_mov_b32_e32 v236, 0x3fe0
	v_mov_b32_e32 v237, 0xf149f2ca
	v_add_f32_e32 v64, v207, v243
	ds_bpermute_b32 v66, v241, v64
	s_mov_b32 s22, 0x3fb8aa3b
	v_add_f32_e32 v65, v244, v245
	ds_bpermute_b32 v67, v241, v65
	s_mov_b32 s2, 0xc2ce8ed0
	s_waitcnt lgkmcnt(1)
	v_add_f32_e32 v64, v64, v66
	v_mul_f32_e32 v66, 0x3fb8aa3b, v64
	v_fma_f32 v68, v64, s22, -v66
	v_rndne_f32_e32 v69, v66
	v_fmac_f32_e32 v68, 0x32a5705f, v64
	v_sub_f32_e32 v66, v66, v69
	v_add_f32_e32 v66, v66, v68
	v_exp_f32_e32 v66, v66
	v_cvt_i32_f32_e32 v68, v69
	v_cmp_ngt_f32_e32 vcc, s2, v64
	s_mov_b32 s3, 0x42b17218
	s_waitcnt lgkmcnt(0)
	v_add_f32_e32 v65, v65, v67
	v_ldexp_f32 v66, v66, v68
	v_cndmask_b32_e32 v66, 0, v66, vcc
	v_cmp_nlt_f32_e32 vcc, s3, v64
	v_lshlrev_b32_e32 v74, 3, v240
	v_mov_b32_e32 v75, v193
	v_cndmask_b32_e32 v64, v233, v66, vcc
	v_mul_f32_e32 v66, 0x3fb8aa3b, v65
	v_fma_f32 v67, v65, s22, -v66
	v_rndne_f32_e32 v68, v66
	v_fmac_f32_e32 v67, 0x32a5705f, v65
	v_sub_f32_e32 v66, v66, v68
	v_add_f32_e32 v66, v66, v67
	v_exp_f32_e32 v66, v66
	v_cvt_i32_f32_e32 v67, v68
	v_cmp_ngt_f32_e32 vcc, s2, v65
	v_ldexp_f32 v66, v66, v67
	s_nop 0
	v_cndmask_b32_e32 v66, 0, v66, vcc
	v_cmp_nlt_f32_e32 vcc, s3, v65
	s_nop 1
	v_cndmask_b32_e32 v65, v233, v66, vcc
	v_sub_f32_e32 v64, v64, v65
	ds_bpermute_b32 v65, v239, v203
	s_waitcnt lgkmcnt(0)
	v_add_f32_e32 v66, v203, v65
	v_div_scale_f32 v67, s[2:3], v66, v66, 1.0
	v_rcp_f32_e32 v68, v67
	ds_bpermute_b32 v65, v239, v199
	v_fma_f32 v69, -v67, v68, 1.0
	v_fmac_f32_e32 v68, v69, v68
	v_div_scale_f32 v69, vcc, 1.0, v66, 1.0
	v_mul_f32_e32 v70, v69, v68
	v_fma_f32 v71, -v67, v70, v69
	v_fmac_f32_e32 v70, v71, v68
	v_fma_f32 v67, -v67, v70, v69
	s_waitcnt lgkmcnt(0)
	v_pk_add_f32 v[64:65], v[198:199], v[64:65]
	v_div_fmas_f32 v67, v67, v68, v70
	v_div_fixup_f32 v68, v67, v66, 1.0
	v_div_scale_f32 v66, s[2:3], v65, v65, v64
	v_rcp_f32_e32 v67, v66
	v_readlane_b32 s2, v253, 31
	v_readlane_b32 s3, v253, 32
	v_fma_f32 v69, -v66, v67, 1.0
	v_fmac_f32_e32 v67, v69, v67
	v_div_scale_f32 v69, vcc, v64, v65, v64
	v_mul_f32_e32 v70, v69, v67
	v_fma_f32 v71, -v66, v70, v69
	v_fmac_f32_e32 v70, v71, v67
	v_fma_f32 v66, -v66, v70, v69
	v_div_fmas_f32 v66, v66, v67, v70
	v_div_fixup_f32 v70, v66, v65, v64
	global_load_dwordx4 v[64:67], v192, s[40:41]
	v_pk_mul_f32 v[32:33], v[32:33], v[70:71] op_sel_hi:[1,0]
	v_pk_mul_f32 v[34:35], v[34:35], v[70:71] op_sel_hi:[1,0]
	v_pk_fma_f32 v[32:33], v[48:49], v[68:69], v[32:33] op_sel_hi:[1,0,1] neg_lo:[0,0,1] neg_hi:[0,0,1]
	v_pk_fma_f32 v[34:35], v[50:51], v[68:69], v[34:35] op_sel_hi:[1,0,1] neg_lo:[0,0,1] neg_hi:[0,0,1]
	v_pk_mul_f32 v[48:49], v[32:33], v[32:33]
	v_pk_mul_f32 v[50:51], v[34:35], v[34:35]
	v_pk_mul_f32 v[36:37], v[36:37], v[70:71] op_sel_hi:[1,0]
	v_add_f32_e32 v48, v48, v49
	v_pk_fma_f32 v[36:37], v[52:53], v[68:69], v[36:37] op_sel_hi:[1,0,1] neg_lo:[0,0,1] neg_hi:[0,0,1]
	v_add_f32_e32 v48, v50, v48
	v_pk_mul_f32 v[38:39], v[38:39], v[70:71] op_sel_hi:[1,0]
	v_pk_mul_f32 v[52:53], v[36:37], v[36:37]
	v_add_f32_e32 v48, v51, v48
	v_pk_fma_f32 v[38:39], v[54:55], v[68:69], v[38:39] op_sel_hi:[1,0,1] neg_lo:[0,0,1] neg_hi:[0,0,1]
	v_add_f32_e32 v48, v52, v48
	v_pk_mul_f32 v[54:55], v[38:39], v[38:39]
	v_pk_mul_f32 v[40:41], v[40:41], v[70:71] op_sel_hi:[1,0]
	v_add_f32_e32 v48, v53, v48
	v_pk_fma_f32 v[40:41], v[56:57], v[68:69], v[40:41] op_sel_hi:[1,0,1] neg_lo:[0,0,1] neg_hi:[0,0,1]
	v_add_f32_e32 v48, v54, v48
	v_pk_mul_f32 v[42:43], v[42:43], v[70:71] op_sel_hi:[1,0]
	v_pk_mul_f32 v[56:57], v[40:41], v[40:41]
	v_add_f32_e32 v48, v55, v48
	v_pk_fma_f32 v[42:43], v[58:59], v[68:69], v[42:43] op_sel_hi:[1,0,1] neg_lo:[0,0,1] neg_hi:[0,0,1]
	v_add_f32_e32 v48, v56, v48
	v_pk_mul_f32 v[58:59], v[42:43], v[42:43]
	v_pk_mul_f32 v[44:45], v[44:45], v[70:71] op_sel_hi:[1,0]
	v_add_f32_e32 v48, v57, v48
	v_pk_fma_f32 v[44:45], v[60:61], v[68:69], v[44:45] op_sel_hi:[1,0,1] neg_lo:[0,0,1] neg_hi:[0,0,1]
	v_add_f32_e32 v48, v58, v48
	v_pk_mul_f32 v[46:47], v[46:47], v[70:71] op_sel_hi:[1,0]
	v_pk_mul_f32 v[60:61], v[44:45], v[44:45]
	v_add_f32_e32 v48, v59, v48
	v_pk_fma_f32 v[46:47], v[62:63], v[68:69], v[46:47] op_sel_hi:[1,0,1] neg_lo:[0,0,1] neg_hi:[0,0,1]
	v_add_f32_e32 v48, v60, v48
	v_pk_mul_f32 v[62:63], v[46:47], v[46:47]
	v_pk_mul_f32 v[0:1], v[0:1], v[70:71] op_sel_hi:[1,0]
	v_add_f32_e32 v48, v61, v48
	v_pk_fma_f32 v[16:17], v[16:17], v[68:69], v[0:1] op_sel_hi:[1,0,1] neg_lo:[0,0,1] neg_hi:[0,0,1]
	v_add_f32_e32 v48, v62, v48
	v_pk_mul_f32 v[2:3], v[2:3], v[70:71] op_sel_hi:[1,0]
	v_pk_mul_f32 v[0:1], v[16:17], v[16:17]
	v_add_f32_e32 v48, v63, v48
	v_pk_fma_f32 v[18:19], v[18:19], v[68:69], v[2:3] op_sel_hi:[1,0,1] neg_lo:[0,0,1] neg_hi:[0,0,1]
	v_add_f32_e32 v0, v0, v48
; DI unsigned pk2(float a, float b) { f32x2 v = {a, b}; return __builtin_bit_cast(unsigned, __builtin_convertvector(v, bf16x2_t)); }
; DI void attnA_block(const Params& p, int layer, unsigned char* smem, int b, int h, int qrow_blk, int ubeg, int uend) {
;     ...
; #pragma unroll
;   for (int dh = 0; dh < 2; ++dh)
; #pragma unroll
;     for (int i = 0; i < 16; ++i) { const float v = o[0][dh][i] * i0 - o[1][dh][i] * c1; o[0][dh][i] = v; ss += v * v; }
;   ss += __shfl_xor(ss, 32);
;   const float r = rsqrtf(ss * (1.f / 64.f) + EPS) * (1.f - lam_init);
;   bf16_t* op = p.MO + (size_t)(qrow0 + qi) * DM + h * 64;
;   const float* sg = p.da_sub_gain + layer * 64;
; #pragma unroll
;   for (int dh = 0; dh < 2; ++dh)
; #pragma unroll
;     for (int g = 0; g < 4; ++g) {
;       const int dv = 32 * dh + 8 * g + 4 * hh;
;       const f32x4 g4 = *(const f32x4*)(sg + dv);
;       u32x2 w;
;       w[0] = pk2(o[0][dh][4 * g] * r * g4[0], o[0][dh][4 * g + 1] * r * g4[1]);
;       w[1] = pk2(o[0][dh][4 * g + 2] * r * g4[2], o[0][dh][4 * g + 3] * r * g4[3]);
;       *(u32x2*)(op + dv) = w;
;     }
; DI void mix_phase(const Params& p, int layer, unsigned char* smem, unsigned char* smem_all, int bid, int nb, int rrank) {
;     ...
;       for (int qb = jj; qb < 64; qb += per_r) attnA_block(p, layer, smem_all, bh >> 2, bh & 3, (bh >> 2) * SEQ + qb * 256, 0, UA);
	v_pk_mul_f32 v[2:3], v[18:19], v[18:19]
	v_pk_mul_f32 v[4:5], v[4:5], v[70:71] op_sel_hi:[1,0]
	v_add_f32_e32 v0, v1, v0
	v_pk_fma_f32 v[4:5], v[20:21], v[68:69], v[4:5] op_sel_hi:[1,0,1] neg_lo:[0,0,1] neg_hi:[0,0,1]
	v_add_f32_e32 v0, v2, v0
	v_pk_mul_f32 v[6:7], v[6:7], v[70:71] op_sel_hi:[1,0]
	v_pk_mul_f32 v[20:21], v[4:5], v[4:5]
	v_add_f32_e32 v0, v3, v0
	v_pk_fma_f32 v[6:7], v[22:23], v[68:69], v[6:7] op_sel_hi:[1,0,1] neg_lo:[0,0,1] neg_hi:[0,0,1]
	v_add_f32_e32 v0, v20, v0
	v_pk_mul_f32 v[22:23], v[6:7], v[6:7]
	v_pk_mul_f32 v[8:9], v[8:9], v[70:71] op_sel_hi:[1,0]
	v_add_f32_e32 v0, v21, v0
	v_pk_fma_f32 v[8:9], v[24:25], v[68:69], v[8:9] op_sel_hi:[1,0,1] neg_lo:[0,0,1] neg_hi:[0,0,1]
	v_add_f32_e32 v0, v22, v0
	v_pk_mul_f32 v[10:11], v[10:11], v[70:71] op_sel_hi:[1,0]
	v_pk_mul_f32 v[24:25], v[8:9], v[8:9]
	v_add_f32_e32 v0, v23, v0
	v_pk_fma_f32 v[10:11], v[26:27], v[68:69], v[10:11] op_sel_hi:[1,0,1] neg_lo:[0,0,1] neg_hi:[0,0,1]
	v_add_f32_e32 v0, v24, v0
	v_pk_mul_f32 v[12:13], v[12:13], v[70:71] op_sel_hi:[1,0]
	v_pk_mul_f32 v[26:27], v[10:11], v[10:11]
	v_add_f32_e32 v0, v25, v0
	v_pk_fma_f32 v[12:13], v[28:29], v[68:69], v[12:13] op_sel_hi:[1,0,1] neg_lo:[0,0,1] neg_hi:[0,0,1]
	v_add_f32_e32 v0, v26, v0
	v_pk_mul_f32 v[72:73], v[12:13], v[12:13]
	v_pk_mul_f32 v[14:15], v[14:15], v[70:71] op_sel_hi:[1,0]
	v_add_f32_e32 v0, v27, v0
	v_pk_fma_f32 v[14:15], v[30:31], v[68:69], v[14:15] op_sel_hi:[1,0,1] neg_lo:[0,0,1] neg_hi:[0,0,1]
	v_add_f32_e32 v0, v72, v0
	v_pk_mul_f32 v[30:31], v[14:15], v[14:15]
	v_add_f32_e32 v0, v73, v0
	v_add_f32_e32 v0, v30, v0
	v_add_f32_e32 v0, v31, v0
	ds_bpermute_b32 v1, v239, v0
	v_lshlrev_b64 v[28:29], 11, v[200:201]
	v_lshl_add_u64 v[28:29], s[2:3], 0, v[28:29]
	s_mov_b32 s2, 0x800000
	v_lshl_add_u64 v[28:29], v[28:29], 0, v[74:75]
	s_waitcnt lgkmcnt(0)
	v_add_f32_e32 v0, v0, v1
	v_fmamk_f32 v0, v0, 0x3c800000, v194
	v_cmp_gt_f32_e32 vcc, s2, v0
	v_mul_f32_e32 v1, 0x4b800000, v0
	v_readlane_b32 s2, v253, 17
	v_cndmask_b32_e32 v0, v0, v1, vcc
	v_rsq_f32_e32 v0, v0
	s_add_i32 s24, s24, s2
	s_cmp_lt_i32 s24, 64
	v_mul_f32_e32 v1, 0x45800000, v0
	v_cndmask_b32_e32 v0, v0, v1, vcc
	v_mul_f32_e32 v20, v197, v0
	v_pk_mul_f32 v[0:1], v[32:33], v[20:21] op_sel_hi:[1,0]
	v_pk_mul_f32 v[2:3], v[34:35], v[20:21] op_sel_hi:[1,0]
	s_waitcnt vmcnt(0)
	v_pk_mul_f32 v[0:1], v[64:65], v[0:1]
	v_pk_mul_f32 v[2:3], v[66:67], v[2:3]
	v_cvt_pk_bf16_f32 v0, v0, v1
	v_cvt_pk_bf16_f32 v1, v2, v3
	global_store_dwordx2 v[28:29], v[0:1], off
	global_load_dwordx4 v[0:3], v192, s[40:41] offset:32
	v_pk_mul_f32 v[22:23], v[36:37], v[20:21] op_sel_hi:[1,0]
	v_pk_mul_f32 v[16:17], v[16:17], v[20:21] op_sel_hi:[1,0]
	v_pk_mul_f32 v[4:5], v[4:5], v[20:21] op_sel_hi:[1,0]
	s_waitcnt vmcnt(0)
	v_pk_mul_f32 v[0:1], v[0:1], v[22:23]
	v_pk_mul_f32 v[22:23], v[38:39], v[20:21] op_sel_hi:[1,0]
	v_cvt_pk_bf16_f32 v0, v0, v1
	v_pk_mul_f32 v[2:3], v[2:3], v[22:23]
	v_pk_mul_f32 v[22:23], v[40:41], v[20:21] op_sel_hi:[1,0]
	v_cvt_pk_bf16_f32 v1, v2, v3
	global_store_dwordx2 v[28:29], v[0:1], off offset:16
	global_load_dwordx4 v[0:3], v192, s[40:41] offset:64
	s_waitcnt vmcnt(0)
	v_pk_mul_f32 v[0:1], v[0:1], v[22:23]
	v_pk_mul_f32 v[22:23], v[42:43], v[20:21] op_sel_hi:[1,0]
	v_cvt_pk_bf16_f32 v0, v0, v1
	v_pk_mul_f32 v[2:3], v[2:3], v[22:23]
	v_pk_mul_f32 v[22:23], v[44:45], v[20:21] op_sel_hi:[1,0]
	v_cvt_pk_bf16_f32 v1, v2, v3
	global_store_dwordx2 v[28:29], v[0:1], off offset:32
	global_load_dwordx4 v[0:3], v192, s[40:41] offset:96
	s_waitcnt vmcnt(0)
	v_pk_mul_f32 v[0:1], v[0:1], v[22:23]
	v_pk_mul_f32 v[22:23], v[46:47], v[20:21] op_sel_hi:[1,0]
	v_cvt_pk_bf16_f32 v0, v0, v1
	v_pk_mul_f32 v[2:3], v[2:3], v[22:23]
	s_nop 0
	v_cvt_pk_bf16_f32 v1, v2, v3
	global_store_dwordx2 v[28:29], v[0:1], off offset:48
	global_load_dwordx4 v[0:3], v192, s[40:41] offset:128
	s_waitcnt vmcnt(0)
	v_pk_mul_f32 v[0:1], v[0:1], v[16:17]
	v_pk_mul_f32 v[16:17], v[18:19], v[20:21] op_sel_hi:[1,0]
	v_cvt_pk_bf16_f32 v0, v0, v1
	v_pk_mul_f32 v[2:3], v[2:3], v[16:17]
	s_nop 0
	v_cvt_pk_bf16_f32 v1, v2, v3
	global_store_dwordx2 v[28:29], v[0:1], off offset:64
	global_load_dwordx4 v[0:3], v192, s[40:41] offset:160
	s_waitcnt vmcnt(0)
	v_pk_mul_f32 v[0:1], v[0:1], v[4:5]
	v_pk_mul_f32 v[4:5], v[6:7], v[20:21] op_sel_hi:[1,0]
	v_cvt_pk_bf16_f32 v0, v0, v1
	v_pk_mul_f32 v[2:3], v[2:3], v[4:5]
	v_pk_mul_f32 v[4:5], v[8:9], v[20:21] op_sel_hi:[1,0]
	v_cvt_pk_bf16_f32 v1, v2, v3
	global_store_dwordx2 v[28:29], v[0:1], off offset:80
	global_load_dwordx4 v[0:3], v192, s[40:41] offset:192
	s_waitcnt vmcnt(0)
	v_pk_mul_f32 v[0:1], v[0:1], v[4:5]
	v_pk_mul_f32 v[4:5], v[10:11], v[20:21] op_sel_hi:[1,0]
	v_cvt_pk_bf16_f32 v0, v0, v1
	v_pk_mul_f32 v[2:3], v[2:3], v[4:5]
	v_pk_mul_f32 v[4:5], v[12:13], v[20:21] op_sel_hi:[1,0]
	v_cvt_pk_bf16_f32 v1, v2, v3
	global_store_dwordx2 v[28:29], v[0:1], off offset:96
	global_load_dwordx4 v[0:3], v192, s[40:41] offset:224
	s_waitcnt vmcnt(0)
	v_pk_mul_f32 v[0:1], v[0:1], v[4:5]
	v_pk_mul_f32 v[4:5], v[14:15], v[20:21] op_sel_hi:[1,0]
	v_cvt_pk_bf16_f32 v0, v0, v1
	v_pk_mul_f32 v[2:3], v[2:3], v[4:5]
	s_nop 0
	v_cvt_pk_bf16_f32 v1, v2, v3
	global_store_dwordx2 v[28:29], v[0:1], off offset:112
	s_cbranch_scc1 .LBB0_286
	v_readlane_b32 s42, v254, 56
	v_readlane_b32 s40, v254, 26
	v_readlane_b32 s43, v254, 57
